# loop-edge rotation plus v operand quarters read after step 0; two wait states restored before every DPP read in the scan loop (swap with the independent y add, or s_nop)
# baseline (speedup 1.0000x reference)
.LBB0_1050:
	ds_read_b128 v[14:17], v0 offset:20480
	ds_read_b128 v[54:57], v89 offset:16384
	ds_read_b128 v[26:29], v89 offset:16640
	ds_read_b128 v[78:81], v89 offset:4096
	ds_read_b128 v[58:61], v89 offset:4352
	ds_read_b128 v[30:33], v89 offset:4608
	ds_read_b128 v[22:25], v90 offset:8704
	ds_read_b128 v[18:21], v89 offset:16896
	v_pk_mul_f32 v[66:67], v[74:75], v[108:109]
	s_waitcnt lgkmcnt(4)
	v_pk_mul_f32 v[78:79], v[14:15], v[78:79] op_sel_hi:[0,1]
	v_pk_fma_f32 v[66:67], v[76:77], v[110:111], v[66:67]
	v_pk_mul_f32 v[80:81], v[14:15], v[80:81] op_sel_hi:[0,1]
	v_add_f32_e32 v66, v66, v67
	v_pk_fma_f32 v[62:63], v[74:75], v[100:101], v[78:79]
	v_pk_fma_f32 v[64:65], v[76:77], v[102:103], v[80:81]
	v_add_f32_dpp v66, v66, v66 quad_perm:[1,0,3,2] row_mask:0xf bank_mask:0xf bound_ctrl:1
	ds_read_b128 v[10:13], v0 offset:20496
	ds_read_b128 v[6:9], v0 offset:20512
	v_add_f32_dpp v66, v66, v66 quad_perm:[2,3,0,1] row_mask:0xf bank_mask:0xf bound_ctrl:1
	ds_read_b128 v[2:5], v0 offset:20528
	v_mov_b32_e32 v0, v17
	v_add_f32_dpp v66, v66, v66 row_half_mirror row_mask:0xf bank_mask:0xf bound_ctrl:1
	s_add_i32 s26, s26, 1
	s_nop 0
	v_add_f32_dpp v66, v66, v66 row_ror:8 row_mask:0xf bank_mask:0xf bound_ctrl:1
	v_pk_fma_f32 v[62:63], v[120:121], v[66:67], v[62:63] op_sel_hi:[1,0,1] neg_lo:[1,0,0] neg_hi:[1,0,0]
	v_pk_fma_f32 v[64:65], v[122:123], v[66:67], v[64:65] op_sel_hi:[1,0,1] neg_lo:[1,0,0] neg_hi:[1,0,0]
	v_pk_mul_f32 v[50:51], v[112:113], v[62:63]
	v_pk_mul_f32 v[46:47], v[104:105], v[62:63]
	v_pk_fma_f32 v[50:51], v[114:115], v[64:65], v[50:51]
	s_waitcnt lgkmcnt(6)
	v_pk_fma_f32 v[66:67], v[14:15], v[58:59], v[46:47] op_sel:[1,0,0]
	v_add_f32_e32 v47, v50, v51
	v_pk_mul_f32 v[48:49], v[106:107], v[64:65]
	v_pk_mul_f32 v[56:57], v[56:57], v[64:65]
	v_add_f32_dpp v68, v47, v47 quad_perm:[1,0,3,2] row_mask:0xf bank_mask:0xf bound_ctrl:1
	v_pk_fma_f32 v[14:15], v[14:15], v[60:61], v[48:49] op_sel:[1,0,0]
	v_pk_fma_f32 v[54:55], v[54:55], v[62:63], v[56:57]
	v_add_f32_dpp v68, v68, v68 quad_perm:[2,3,0,1] row_mask:0xf bank_mask:0xf bound_ctrl:1
	v_add_f32_e32 v92, v54, v55
	s_nop 0
	v_add_f32_dpp v68, v68, v68 row_half_mirror row_mask:0xf bank_mask:0xf bound_ctrl:1
	ds_read_b128 v[46:49], v90 offset:768
	ds_read_b128 v[50:53], v89 offset:4864
	ds_read_b128 v[54:57], v90 offset:4864
	ds_read_b128 v[58:61], v90 offset:8960
	ds_read_b128 v[62:65], v89 offset:17152
	v_add_f32_dpp v68, v68, v68 row_ror:8 row_mask:0xf bank_mask:0xf bound_ctrl:1
	v_pk_fma_f32 v[42:43], v[128:129], v[68:69], v[66:67] op_sel_hi:[1,0,1] neg_lo:[1,0,0] neg_hi:[1,0,0]
	v_pk_fma_f32 v[14:15], v[130:131], v[68:69], v[14:15] op_sel_hi:[1,0,1] neg_lo:[1,0,0] neg_hi:[1,0,0]
	v_pk_mul_f32 v[38:39], v[124:125], v[42:43]
	v_pk_mul_f32 v[28:29], v[28:29], v[14:15]
	v_pk_mul_f32 v[36:37], v[118:119], v[14:15]
	v_pk_fma_f32 v[14:15], v[126:127], v[14:15], v[38:39]
	v_pk_mul_f32 v[34:35], v[116:117], v[42:43]
	v_add_f32_e32 v14, v14, v15
	v_pk_fma_f32 v[26:27], v[26:27], v[42:43], v[28:29]
	s_waitcnt lgkmcnt(10)
	v_pk_fma_f32 v[42:43], v[16:17], v[30:31], v[34:35] op_sel_hi:[0,1,1]
	v_add_f32_dpp v66, v14, v14 quad_perm:[1,0,3,2] row_mask:0xf bank_mask:0xf bound_ctrl:1
	v_pk_fma_f32 v[44:45], v[16:17], v[32:33], v[36:37] op_sel_hi:[0,1,1]
	v_add_f32_e32 v93, v26, v27
	v_add_f32_dpp v66, v66, v66 quad_perm:[2,3,0,1] row_mask:0xf bank_mask:0xf bound_ctrl:1
	ds_read_b128 v[14:17], v90 offset:1024
	ds_read_b128 v[26:29], v89 offset:5120
	ds_read_b128 v[30:33], v90 offset:5120
	ds_read_b128 v[34:37], v90 offset:9216
	ds_read_b128 v[38:41], v89 offset:17408
	v_add_f32_dpp v66, v66, v66 row_half_mirror row_mask:0xf bank_mask:0xf bound_ctrl:1
	s_nop 1
	v_add_f32_dpp v66, v66, v66 row_ror:8 row_mask:0xf bank_mask:0xf bound_ctrl:1
	s_waitcnt lgkmcnt(14)
	v_pk_fma_f32 v[22:23], v[22:23], v[66:67], v[42:43] op_sel_hi:[1,0,1] neg_lo:[1,0,0] neg_hi:[1,0,0]
	v_pk_fma_f32 v[24:25], v[24:25], v[66:67], v[44:45] op_sel_hi:[1,0,1] neg_lo:[1,0,0] neg_hi:[1,0,0]
	s_waitcnt lgkmcnt(7)
	v_pk_mul_f32 v[42:43], v[54:55], v[22:23]
	v_pk_mul_f32 v[20:21], v[20:21], v[24:25]
	v_pk_mul_f32 v[44:45], v[46:47], v[22:23]
	v_pk_mul_f32 v[46:47], v[48:49], v[24:25]
	v_pk_fma_f32 v[18:19], v[18:19], v[22:23], v[20:21]
	v_pk_fma_f32 v[20:21], v[56:57], v[24:25], v[42:43]
	v_pk_fma_f32 v[54:55], v[0:1], v[50:51], v[44:45] op_sel_hi:[0,1,1]
	v_pk_fma_f32 v[56:57], v[0:1], v[52:53], v[46:47] op_sel_hi:[0,1,1]
	v_add_f32_e32 v94, v18, v19
	v_add_f32_e32 v18, v20, v21
	v_mov_b32_e32 v82, v13
	v_mov_b32_e32 v84, v9
	v_mov_b32_e32 v86, v5
	s_nop 0
	v_add_f32_dpp v0, v18, v18 quad_perm:[1,0,3,2] row_mask:0xf bank_mask:0xf bound_ctrl:1
	ds_read_b128 v[18:21], v90 offset:1280
	ds_read_b128 v[22:25], v89 offset:5376
	v_add_f32_dpp v0, v0, v0 quad_perm:[2,3,0,1] row_mask:0xf bank_mask:0xf bound_ctrl:1
	ds_read_b128 v[42:45], v90 offset:5376
	ds_read_b128 v[46:49], v90 offset:9472
	v_add_f32_dpp v0, v0, v0 row_half_mirror row_mask:0xf bank_mask:0xf bound_ctrl:1
	ds_read_b128 v[50:53], v89 offset:17664
	s_nop 0
	v_add_f32_dpp v0, v0, v0 row_ror:8 row_mask:0xf bank_mask:0xf bound_ctrl:1
	s_waitcnt lgkmcnt(11)
	v_pk_fma_f32 v[54:55], v[58:59], v[0:1], v[54:55] op_sel_hi:[1,0,1] neg_lo:[1,0,0] neg_hi:[1,0,0]
	v_pk_fma_f32 v[56:57], v[60:61], v[0:1], v[56:57] op_sel_hi:[1,0,1] neg_lo:[1,0,0] neg_hi:[1,0,0]
	s_waitcnt lgkmcnt(7)
	v_pk_mul_f32 v[30:31], v[30:31], v[54:55]
	v_pk_mul_f32 v[58:59], v[64:65], v[56:57]
	v_pk_mul_f32 v[14:15], v[14:15], v[54:55]
	v_pk_fma_f32 v[54:55], v[62:63], v[54:55], v[58:59]
	v_pk_fma_f32 v[30:31], v[32:33], v[56:57], v[30:31]
	v_pk_fma_f32 v[62:63], v[10:11], v[26:27], v[14:15] op_sel_hi:[0,1,1]
	v_add_f32_e32 v95, v54, v55
	v_add_f32_e32 v14, v30, v31
	ds_write_b128 v91, v[92:95] offset:43008
	v_pk_mul_f32 v[16:17], v[16:17], v[56:57]
	v_add_f32_dpp v0, v14, v14 quad_perm:[1,0,3,2] row_mask:0xf bank_mask:0xf bound_ctrl:1
	v_pk_fma_f32 v[64:65], v[10:11], v[28:29], v[16:17] op_sel_hi:[0,1,1]
	ds_read_b128 v[14:17], v90 offset:1536
	v_add_f32_dpp v0, v0, v0 quad_perm:[2,3,0,1] row_mask:0xf bank_mask:0xf bound_ctrl:1
	ds_read_b128 v[26:29], v89 offset:5632
	ds_read_b128 v[30:33], v90 offset:5632
	v_add_f32_dpp v0, v0, v0 row_half_mirror row_mask:0xf bank_mask:0xf bound_ctrl:1
	ds_read_b128 v[54:57], v90 offset:9728
	ds_read_b128 v[58:61], v89 offset:17920
	v_add_f32_dpp v0, v0, v0 row_ror:8 row_mask:0xf bank_mask:0xf bound_ctrl:1
	s_waitcnt lgkmcnt(12)
	v_pk_fma_f32 v[34:35], v[34:35], v[0:1], v[62:63] op_sel_hi:[1,0,1] neg_lo:[1,0,0] neg_hi:[1,0,0]
	v_pk_fma_f32 v[36:37], v[36:37], v[0:1], v[64:65] op_sel_hi:[1,0,1] neg_lo:[1,0,0] neg_hi:[1,0,0]
	s_waitcnt lgkmcnt(8)
	v_pk_mul_f32 v[42:43], v[42:43], v[34:35]
	v_pk_mul_f32 v[40:41], v[40:41], v[36:37]
	v_pk_mul_f32 v[18:19], v[18:19], v[34:35]
	v_pk_mul_f32 v[20:21], v[20:21], v[36:37]
	v_pk_fma_f32 v[34:35], v[38:39], v[34:35], v[40:41]
	v_pk_fma_f32 v[36:37], v[44:45], v[36:37], v[42:43]
	v_pk_fma_f32 v[62:63], v[10:11], v[22:23], v[18:19] op_sel:[1,0,0]
	v_add_f32_e32 v18, v36, v37
	v_add_f32_e32 v96, v34, v35
	v_pk_fma_f32 v[10:11], v[10:11], v[24:25], v[20:21] op_sel:[1,0,0]
	v_add_f32_dpp v0, v18, v18 quad_perm:[1,0,3,2] row_mask:0xf bank_mask:0xf bound_ctrl:1
	ds_read_b128 v[18:21], v90 offset:1792
	ds_read_b128 v[22:25], v89 offset:5888
	v_add_f32_dpp v0, v0, v0 quad_perm:[2,3,0,1] row_mask:0xf bank_mask:0xf bound_ctrl:1
	ds_read_b128 v[34:37], v90 offset:5888
	ds_read_b128 v[38:41], v90 offset:9984
	v_add_f32_dpp v0, v0, v0 row_half_mirror row_mask:0xf bank_mask:0xf bound_ctrl:1
	ds_read_b128 v[42:45], v89 offset:18176
	s_nop 0
	v_add_f32_dpp v0, v0, v0 row_ror:8 row_mask:0xf bank_mask:0xf bound_ctrl:1
	s_waitcnt lgkmcnt(12)
	v_pk_fma_f32 v[46:47], v[46:47], v[0:1], v[62:63] op_sel_hi:[1,0,1] neg_lo:[1,0,0] neg_hi:[1,0,0]
	v_pk_fma_f32 v[10:11], v[48:49], v[0:1], v[10:11] op_sel_hi:[1,0,1] neg_lo:[1,0,0] neg_hi:[1,0,0]
	s_waitcnt lgkmcnt(7)
	v_pk_mul_f32 v[30:31], v[30:31], v[46:47]
	v_pk_mul_f32 v[48:49], v[52:53], v[10:11]
	v_pk_mul_f32 v[14:15], v[14:15], v[46:47]
	v_pk_mul_f32 v[16:17], v[16:17], v[10:11]
	v_pk_fma_f32 v[46:47], v[50:51], v[46:47], v[48:49]
	v_pk_fma_f32 v[10:11], v[32:33], v[10:11], v[30:31]
	v_add_f32_e32 v10, v10, v11
	v_add_f32_e32 v97, v46, v47
	v_pk_fma_f32 v[50:51], v[12:13], v[26:27], v[14:15] op_sel_hi:[0,1,1]
	v_add_f32_dpp v0, v10, v10 quad_perm:[1,0,3,2] row_mask:0xf bank_mask:0xf bound_ctrl:1
	v_pk_fma_f32 v[52:53], v[12:13], v[28:29], v[16:17] op_sel_hi:[0,1,1]
	ds_read_b128 v[10:13], v90 offset:2048
	v_add_f32_dpp v0, v0, v0 quad_perm:[2,3,0,1] row_mask:0xf bank_mask:0xf bound_ctrl:1
	ds_read_b128 v[14:17], v89 offset:6144
	ds_read_b128 v[26:29], v90 offset:6144
	v_add_f32_dpp v0, v0, v0 row_half_mirror row_mask:0xf bank_mask:0xf bound_ctrl:1
	ds_read_b128 v[30:33], v90 offset:10240
	ds_read_b128 v[46:49], v89 offset:18432
	v_add_f32_dpp v0, v0, v0 row_ror:8 row_mask:0xf bank_mask:0xf bound_ctrl:1
	s_waitcnt lgkmcnt(11)
	v_pk_fma_f32 v[50:51], v[54:55], v[0:1], v[50:51] op_sel_hi:[1,0,1] neg_lo:[1,0,0] neg_hi:[1,0,0]
	v_pk_fma_f32 v[52:53], v[56:57], v[0:1], v[52:53] op_sel_hi:[1,0,1] neg_lo:[1,0,0] neg_hi:[1,0,0]
	s_waitcnt lgkmcnt(7)
	v_pk_mul_f32 v[34:35], v[34:35], v[50:51]
	v_pk_mul_f32 v[54:55], v[60:61], v[52:53]
	v_pk_mul_f32 v[18:19], v[18:19], v[50:51]
	v_pk_fma_f32 v[50:51], v[58:59], v[50:51], v[54:55]
	v_pk_fma_f32 v[34:35], v[36:37], v[52:53], v[34:35]
	v_pk_fma_f32 v[58:59], v[82:83], v[22:23], v[18:19] op_sel_hi:[0,1,1]
	v_add_f32_e32 v18, v34, v35
	v_add_f32_e32 v98, v50, v51
	v_pk_mul_f32 v[20:21], v[20:21], v[52:53]
	v_add_f32_dpp v0, v18, v18 quad_perm:[1,0,3,2] row_mask:0xf bank_mask:0xf bound_ctrl:1
	v_pk_fma_f32 v[60:61], v[82:83], v[24:25], v[20:21] op_sel_hi:[0,1,1]
	ds_read_b128 v[18:21], v90 offset:2304
	v_add_f32_dpp v0, v0, v0 quad_perm:[2,3,0,1] row_mask:0xf bank_mask:0xf bound_ctrl:1
	ds_read_b128 v[22:25], v89 offset:6400
	ds_read_b128 v[34:37], v90 offset:6400
	v_add_f32_dpp v0, v0, v0 row_half_mirror row_mask:0xf bank_mask:0xf bound_ctrl:1
	ds_read_b128 v[50:53], v90 offset:10496
	ds_read_b128 v[54:57], v89 offset:18688
	v_add_f32_dpp v0, v0, v0 row_ror:8 row_mask:0xf bank_mask:0xf bound_ctrl:1
	s_waitcnt lgkmcnt(11)
	v_pk_fma_f32 v[38:39], v[38:39], v[0:1], v[58:59] op_sel_hi:[1,0,1] neg_lo:[1,0,0] neg_hi:[1,0,0]
	v_pk_fma_f32 v[40:41], v[40:41], v[0:1], v[60:61] op_sel_hi:[1,0,1] neg_lo:[1,0,0] neg_hi:[1,0,0]
	s_waitcnt lgkmcnt(7)
	v_pk_mul_f32 v[26:27], v[26:27], v[38:39]
	v_pk_mul_f32 v[44:45], v[44:45], v[40:41]
	v_pk_mul_f32 v[10:11], v[10:11], v[38:39]
	v_pk_fma_f32 v[38:39], v[42:43], v[38:39], v[44:45]
	v_pk_fma_f32 v[26:27], v[28:29], v[40:41], v[26:27]
	v_pk_fma_f32 v[58:59], v[6:7], v[14:15], v[10:11] op_sel_hi:[0,1,1]
	v_add_f32_e32 v99, v38, v39
	v_add_f32_e32 v10, v26, v27
	ds_write_b128 v91, v[96:99] offset:47104
	v_pk_mul_f32 v[12:13], v[12:13], v[40:41]
	v_add_f32_dpp v0, v10, v10 quad_perm:[1,0,3,2] row_mask:0xf bank_mask:0xf bound_ctrl:1
	v_pk_fma_f32 v[60:61], v[6:7], v[16:17], v[12:13] op_sel_hi:[0,1,1]
	ds_read_b128 v[10:13], v90 offset:2560
	v_add_f32_dpp v0, v0, v0 quad_perm:[2,3,0,1] row_mask:0xf bank_mask:0xf bound_ctrl:1
	ds_read_b128 v[14:17], v89 offset:6656
	ds_read_b128 v[26:29], v90 offset:6656
	v_add_f32_dpp v0, v0, v0 row_half_mirror row_mask:0xf bank_mask:0xf bound_ctrl:1
	ds_read_b128 v[38:41], v90 offset:10752
	ds_read_b128 v[42:45], v89 offset:18944
	v_add_f32_dpp v0, v0, v0 row_ror:8 row_mask:0xf bank_mask:0xf bound_ctrl:1
	s_waitcnt lgkmcnt(12)
	v_pk_fma_f32 v[30:31], v[30:31], v[0:1], v[58:59] op_sel_hi:[1,0,1] neg_lo:[1,0,0] neg_hi:[1,0,0]
	v_pk_fma_f32 v[32:33], v[32:33], v[0:1], v[60:61] op_sel_hi:[1,0,1] neg_lo:[1,0,0] neg_hi:[1,0,0]
	s_waitcnt lgkmcnt(8)
	v_pk_mul_f32 v[34:35], v[34:35], v[30:31]
	v_pk_mul_f32 v[48:49], v[48:49], v[32:33]
	v_pk_mul_f32 v[18:19], v[18:19], v[30:31]
	v_pk_mul_f32 v[20:21], v[20:21], v[32:33]
	v_pk_fma_f32 v[30:31], v[46:47], v[30:31], v[48:49]
	v_pk_fma_f32 v[32:33], v[36:37], v[32:33], v[34:35]
	v_pk_fma_f32 v[58:59], v[6:7], v[22:23], v[18:19] op_sel:[1,0,0]
	v_add_f32_e32 v18, v32, v33
	v_add_f32_e32 v92, v30, v31
	v_pk_fma_f32 v[6:7], v[6:7], v[24:25], v[20:21] op_sel:[1,0,0]
	v_add_f32_dpp v0, v18, v18 quad_perm:[1,0,3,2] row_mask:0xf bank_mask:0xf bound_ctrl:1
	ds_read_b128 v[18:21], v90 offset:2816
	ds_read_b128 v[22:25], v89 offset:6912
	v_add_f32_dpp v0, v0, v0 quad_perm:[2,3,0,1] row_mask:0xf bank_mask:0xf bound_ctrl:1
	ds_read_b128 v[30:33], v90 offset:6912
	ds_read_b128 v[34:37], v90 offset:11008
	v_add_f32_dpp v0, v0, v0 row_half_mirror row_mask:0xf bank_mask:0xf bound_ctrl:1
	ds_read_b128 v[46:49], v89 offset:19200
	s_nop 0
	v_add_f32_dpp v0, v0, v0 row_ror:8 row_mask:0xf bank_mask:0xf bound_ctrl:1
	s_waitcnt lgkmcnt(12)
	v_pk_fma_f32 v[50:51], v[50:51], v[0:1], v[58:59] op_sel_hi:[1,0,1] neg_lo:[1,0,0] neg_hi:[1,0,0]
	v_pk_fma_f32 v[6:7], v[52:53], v[0:1], v[6:7] op_sel_hi:[1,0,1] neg_lo:[1,0,0] neg_hi:[1,0,0]
	s_waitcnt lgkmcnt(7)
	v_pk_mul_f32 v[26:27], v[26:27], v[50:51]
	v_pk_mul_f32 v[52:53], v[56:57], v[6:7]
	v_pk_mul_f32 v[10:11], v[10:11], v[50:51]
	v_pk_mul_f32 v[12:13], v[12:13], v[6:7]
	v_pk_fma_f32 v[50:51], v[54:55], v[50:51], v[52:53]
	v_pk_fma_f32 v[6:7], v[28:29], v[6:7], v[26:27]
	v_add_f32_e32 v6, v6, v7
	v_add_f32_e32 v93, v50, v51
	v_pk_fma_f32 v[54:55], v[8:9], v[14:15], v[10:11] op_sel_hi:[0,1,1]
	v_add_f32_dpp v0, v6, v6 quad_perm:[1,0,3,2] row_mask:0xf bank_mask:0xf bound_ctrl:1
	v_pk_fma_f32 v[56:57], v[8:9], v[16:17], v[12:13] op_sel_hi:[0,1,1]
	ds_read_b128 v[6:9], v90 offset:3072
	v_add_f32_dpp v0, v0, v0 quad_perm:[2,3,0,1] row_mask:0xf bank_mask:0xf bound_ctrl:1
	ds_read_b128 v[10:13], v89 offset:7168
	ds_read_b128 v[14:17], v90 offset:7168
	v_add_f32_dpp v0, v0, v0 row_half_mirror row_mask:0xf bank_mask:0xf bound_ctrl:1
	ds_read_b128 v[26:29], v90 offset:11264
	ds_read_b128 v[50:53], v89 offset:19456
	v_add_f32_dpp v0, v0, v0 row_ror:8 row_mask:0xf bank_mask:0xf bound_ctrl:1
	s_waitcnt lgkmcnt(11)
	v_pk_fma_f32 v[38:39], v[38:39], v[0:1], v[54:55] op_sel_hi:[1,0,1] neg_lo:[1,0,0] neg_hi:[1,0,0]
	v_pk_fma_f32 v[40:41], v[40:41], v[0:1], v[56:57] op_sel_hi:[1,0,1] neg_lo:[1,0,0] neg_hi:[1,0,0]
	s_waitcnt lgkmcnt(7)
	v_pk_mul_f32 v[30:31], v[30:31], v[38:39]
	v_pk_mul_f32 v[44:45], v[44:45], v[40:41]
	v_pk_mul_f32 v[18:19], v[18:19], v[38:39]
	v_pk_fma_f32 v[38:39], v[42:43], v[38:39], v[44:45]
	v_pk_fma_f32 v[30:31], v[32:33], v[40:41], v[30:31]
	v_pk_fma_f32 v[54:55], v[84:85], v[22:23], v[18:19] op_sel_hi:[0,1,1]
	v_add_f32_e32 v18, v30, v31
	v_add_f32_e32 v94, v38, v39
	v_pk_mul_f32 v[20:21], v[20:21], v[40:41]
	v_add_f32_dpp v0, v18, v18 quad_perm:[1,0,3,2] row_mask:0xf bank_mask:0xf bound_ctrl:1
	v_pk_fma_f32 v[56:57], v[84:85], v[24:25], v[20:21] op_sel_hi:[0,1,1]
	ds_read_b128 v[18:21], v90 offset:3328
	v_add_f32_dpp v0, v0, v0 quad_perm:[2,3,0,1] row_mask:0xf bank_mask:0xf bound_ctrl:1
	ds_read_b128 v[22:25], v89 offset:7424
	ds_read_b128 v[30:33], v90 offset:7424
	v_add_f32_dpp v0, v0, v0 row_half_mirror row_mask:0xf bank_mask:0xf bound_ctrl:1
	ds_read_b128 v[38:41], v90 offset:11520
	ds_read_b128 v[42:45], v89 offset:19712
	v_add_f32_dpp v0, v0, v0 row_ror:8 row_mask:0xf bank_mask:0xf bound_ctrl:1
	s_waitcnt lgkmcnt(11)
	v_pk_fma_f32 v[34:35], v[34:35], v[0:1], v[54:55] op_sel_hi:[1,0,1] neg_lo:[1,0,0] neg_hi:[1,0,0]
	v_pk_fma_f32 v[36:37], v[36:37], v[0:1], v[56:57] op_sel_hi:[1,0,1] neg_lo:[1,0,0] neg_hi:[1,0,0]
	s_waitcnt lgkmcnt(7)
	v_pk_mul_f32 v[14:15], v[14:15], v[34:35]
	v_pk_mul_f32 v[48:49], v[48:49], v[36:37]
	v_pk_mul_f32 v[6:7], v[6:7], v[34:35]
	v_pk_fma_f32 v[34:35], v[46:47], v[34:35], v[48:49]
	v_pk_fma_f32 v[14:15], v[16:17], v[36:37], v[14:15]
	v_pk_fma_f32 v[54:55], v[2:3], v[10:11], v[6:7] op_sel_hi:[0,1,1]
	v_add_f32_e32 v95, v34, v35
	v_add_f32_e32 v6, v14, v15
	ds_write_b128 v91, v[92:95] offset:51200
	v_pk_mul_f32 v[8:9], v[8:9], v[36:37]
	v_add_f32_dpp v0, v6, v6 quad_perm:[1,0,3,2] row_mask:0xf bank_mask:0xf bound_ctrl:1
	v_pk_fma_f32 v[56:57], v[2:3], v[12:13], v[8:9] op_sel_hi:[0,1,1]
	ds_read_b128 v[6:9], v90 offset:3584
	v_add_f32_dpp v0, v0, v0 quad_perm:[2,3,0,1] row_mask:0xf bank_mask:0xf bound_ctrl:1
	ds_read_b128 v[10:13], v89 offset:7680
	ds_read_b128 v[14:17], v90 offset:7680
	v_add_f32_dpp v0, v0, v0 row_half_mirror row_mask:0xf bank_mask:0xf bound_ctrl:1
	ds_read_b128 v[34:37], v90 offset:11776
	ds_read_b128 v[46:49], v89 offset:19968
	v_add_f32_dpp v0, v0, v0 row_ror:8 row_mask:0xf bank_mask:0xf bound_ctrl:1
	s_waitcnt lgkmcnt(12)
	v_pk_fma_f32 v[26:27], v[26:27], v[0:1], v[54:55] op_sel_hi:[1,0,1] neg_lo:[1,0,0] neg_hi:[1,0,0]
	v_pk_fma_f32 v[28:29], v[28:29], v[0:1], v[56:57] op_sel_hi:[1,0,1] neg_lo:[1,0,0] neg_hi:[1,0,0]
	s_waitcnt lgkmcnt(8)
	v_pk_mul_f32 v[30:31], v[30:31], v[26:27]
	v_pk_mul_f32 v[52:53], v[52:53], v[28:29]
	v_pk_mul_f32 v[18:19], v[18:19], v[26:27]
	v_pk_mul_f32 v[20:21], v[20:21], v[28:29]
	v_pk_fma_f32 v[26:27], v[50:51], v[26:27], v[52:53]
	v_pk_fma_f32 v[28:29], v[32:33], v[28:29], v[30:31]
	v_pk_fma_f32 v[54:55], v[2:3], v[22:23], v[18:19] op_sel:[1,0,0]
	v_add_f32_e32 v18, v28, v29
	v_add_f32_e32 v96, v26, v27
	v_pk_fma_f32 v[2:3], v[2:3], v[24:25], v[20:21] op_sel:[1,0,0]
	v_add_f32_dpp v0, v18, v18 quad_perm:[1,0,3,2] row_mask:0xf bank_mask:0xf bound_ctrl:1
	ds_read_b128 v[18:21], v90 offset:3840
	ds_read_b128 v[22:25], v89 offset:7936
	v_add_f32_dpp v0, v0, v0 quad_perm:[2,3,0,1] row_mask:0xf bank_mask:0xf bound_ctrl:1
	ds_read_b128 v[26:29], v90 offset:7936
	ds_read_b128 v[30:33], v90 offset:12032
	v_add_f32_dpp v0, v0, v0 row_half_mirror row_mask:0xf bank_mask:0xf bound_ctrl:1
	ds_read_b128 v[50:53], v89 offset:20224
	s_nop 0
	v_add_f32_dpp v0, v0, v0 row_ror:8 row_mask:0xf bank_mask:0xf bound_ctrl:1
	s_waitcnt lgkmcnt(12)
	v_pk_fma_f32 v[38:39], v[38:39], v[0:1], v[54:55] op_sel_hi:[1,0,1] neg_lo:[1,0,0] neg_hi:[1,0,0]
	v_pk_fma_f32 v[2:3], v[40:41], v[0:1], v[2:3] op_sel_hi:[1,0,1] neg_lo:[1,0,0] neg_hi:[1,0,0]
	s_waitcnt lgkmcnt(7)
	v_pk_mul_f32 v[14:15], v[14:15], v[38:39]
	v_pk_mul_f32 v[40:41], v[44:45], v[2:3]
	v_pk_mul_f32 v[8:9], v[8:9], v[2:3]
	v_pk_fma_f32 v[2:3], v[16:17], v[2:3], v[14:15]
	v_pk_mul_f32 v[6:7], v[6:7], v[38:39]
	v_add_f32_e32 v0, v2, v3
	v_pk_fma_f32 v[6:7], v[4:5], v[10:11], v[6:7] op_sel_hi:[0,1,1]
	v_pk_fma_f32 v[4:5], v[4:5], v[12:13], v[8:9] op_sel_hi:[0,1,1]
	v_add_f32_dpp v0, v0, v0 quad_perm:[1,0,3,2] row_mask:0xf bank_mask:0xf bound_ctrl:1
	v_pk_fma_f32 v[38:39], v[42:43], v[38:39], v[40:41]
	ds_read_b128 v[108:111], v88 offset:4096
	v_add_f32_dpp v0, v0, v0 quad_perm:[2,3,0,1] row_mask:0xf bank_mask:0xf bound_ctrl:1
	v_add_f32_e32 v97, v38, v39
	ds_read_b128 v[100:103], v88
	v_add_f32_dpp v0, v0, v0 row_half_mirror row_mask:0xf bank_mask:0xf bound_ctrl:1
	ds_read_b128 v[120:123], v88 offset:8192
	ds_read_b128 v[112:115], v88 offset:4352
	v_add_f32_dpp v0, v0, v0 row_ror:8 row_mask:0xf bank_mask:0xf bound_ctrl:1
	s_waitcnt lgkmcnt(10)
	v_pk_fma_f32 v[2:3], v[34:35], v[0:1], v[6:7] op_sel_hi:[1,0,1] neg_lo:[1,0,0] neg_hi:[1,0,0]
	v_pk_fma_f32 v[4:5], v[36:37], v[0:1], v[4:5] op_sel_hi:[1,0,1] neg_lo:[1,0,0] neg_hi:[1,0,0]
	s_waitcnt lgkmcnt(6)
	v_pk_mul_f32 v[8:9], v[26:27], v[2:3]
	v_pk_mul_f32 v[6:7], v[48:49], v[4:5]
	v_pk_mul_f32 v[10:11], v[18:19], v[2:3]
	v_pk_mul_f32 v[12:13], v[20:21], v[4:5]
	v_pk_fma_f32 v[2:3], v[46:47], v[2:3], v[6:7]
	v_pk_fma_f32 v[4:5], v[28:29], v[4:5], v[8:9]
	v_add_f32_e32 v98, v2, v3
	v_add_f32_e32 v2, v4, v5
	v_pk_fma_f32 v[8:9], v[86:87], v[24:25], v[12:13] op_sel_hi:[0,1,1]
	s_nop 0
	v_add_f32_dpp v0, v2, v2 quad_perm:[1,0,3,2] row_mask:0xf bank_mask:0xf bound_ctrl:1
	v_pk_fma_f32 v[6:7], v[86:87], v[22:23], v[10:11] op_sel_hi:[0,1,1]
	ds_read_b128 v[104:107], v88 offset:256
	v_add_f32_dpp v0, v0, v0 quad_perm:[2,3,0,1] row_mask:0xf bank_mask:0xf bound_ctrl:1
	ds_read_b128 v[128:131], v88 offset:8448
	ds_read_b128 v[124:127], v88 offset:4608
	v_add_f32_dpp v0, v0, v0 row_half_mirror row_mask:0xf bank_mask:0xf bound_ctrl:1
	ds_read_b128 v[116:119], v88 offset:512
	s_nop 0
	v_add_f32_dpp v0, v0, v0 row_ror:8 row_mask:0xf bank_mask:0xf bound_ctrl:1
	s_waitcnt lgkmcnt(9)
	v_pk_fma_f32 v[76:77], v[32:33], v[0:1], v[8:9] op_sel_hi:[1,0,1] neg_lo:[1,0,0] neg_hi:[1,0,0]
	v_pk_fma_f32 v[74:75], v[30:31], v[0:1], v[6:7] op_sel_hi:[1,0,1] neg_lo:[1,0,0] neg_hi:[1,0,0]
	s_waitcnt lgkmcnt(8)
	v_pk_mul_f32 v[2:3], v[52:53], v[76:77]
	s_nop 0
	v_pk_fma_f32 v[2:3], v[50:51], v[74:75], v[2:3]
	s_nop 0
	v_add_f32_e32 v99, v2, v3
	ds_write_b128 v91, v[96:99] offset:55296
	s_and_b32 s2, s26, 1
	s_mul_i32 s3, s2, 0x5400
	v_lshlrev_b32_e32 v91, 2, v87
	v_lshl_add_u32 v91, s2, 14, v91
	s_add_i32 s2, s3, 0
	v_add_u32_e32 v0, s2, v85
	v_add_u32_e32 v89, s2, v83
	v_add_u32_e32 v90, s96, v83
	s_add_i32 s96, s96, 0x3000
	s_cmp_eq_u32 s96, 0x1e800
	s_cselect_b32 s96, 0x20200, s96
	s_cmp_eq_u32 s96, 0x23200
	s_cselect_b32 s96, 0x12800, s96
	v_add_u32_e32 v88, s96, v83
	s_cmpk_eq_i32 s26, 0x110
	s_waitcnt lgkmcnt(0)
	s_barrier
	s_cbranch_scc0 .LBB0_1050
	s_setprio 0
